# v36 + conv: tile load as 16 LDS-DMA (global_load_lds_dwordx4) pieces in flight, no VGPR staging / ds_write
# speedup vs baseline: 1.0159x; 1.0066x over previous
; #define LAS __attribute__((address_space(3)))
; __device__ __forceinline__ void conv_phase(LAS unsigned char* lds, const bf16* U, const float* state, const float* wdw, const float* bdw, const float* lng, const float* lnb, bf16* Z, int blk, int nblk, int tid) {
;     ...
;         if (p0 >= 32) {
;             const char* ub = (const char*)(U + (size_t)(base + p0 - 32) * 1024); const unsigned voff = (unsigned)(tid >> 7) * 2048u + (unsigned)(tid & 127) * 16u;
; #pragma unroll
;             for (int hb = 0; hb < 2; ++hb) { u32x4 tv[8];
; #pragma unroll
;                 for (int k = 0; k < 8; ++k) tv[k] = *(const u32x4*)(ub + (size_t)(8 * hb + k) * 8192 + voff);
; #pragma unroll
;                 for (int k = 0; k < 8; ++k) *(LAS u32x4*)(lds + (size_t)(8 * hb + k) * 8192 + voff) = tv[k]; }
.LBB0_181:
	s_and_b64 vcc, exec, s[4:5]
	s_cbranch_vccz .LBB0_183
	s_add_u32 s2, s2, s15
	s_addc_u32 s3, s3, 0
	s_lshl_b64 s[2:3], s[2:3], 11
	s_add_u32 s2, s6, s2
	s_addc_u32 s3, s7, s3
	v_lshl_add_u64 v[110:111], s[2:3], 0, v[76:77]
	s_lshl_b32 s100, s85, 4
	s_mov_b32 s2, 0xffff0000
	v_add_co_u32_e32 v62, vcc, s2, v110
	s_nop 1
	v_addc_co_u32_e32 v63, vcc, -1, v111, vcc
	s_mov_b32 s2, 0xffff2000
	v_add_co_u32_e32 v82, vcc, s2, v110
	s_nop 1
	v_addc_co_u32_e32 v83, vcc, -1, v111, vcc
	s_mov_b32 s2, 0xffff4000
	v_add_co_u32_e32 v84, vcc, s2, v110
	s_nop 1
	v_addc_co_u32_e32 v85, vcc, -1, v111, vcc
	s_mov_b32 s2, 0xffff6000
	v_add_co_u32_e32 v86, vcc, s2, v110
	s_nop 1
	v_addc_co_u32_e32 v87, vcc, -1, v111, vcc
	s_mov_b32 s2, 0xffff8000
	v_add_co_u32_e32 v88, vcc, s2, v110
	s_nop 1
	v_addc_co_u32_e32 v89, vcc, -1, v111, vcc
	s_mov_b32 s2, 0xffffa000
	v_add_co_u32_e32 v90, vcc, s2, v110
	s_nop 1
	v_addc_co_u32_e32 v91, vcc, -1, v111, vcc
	s_mov_b32 s2, 0xffffc000
	v_add_co_u32_e32 v92, vcc, s2, v110
	s_nop 1
	v_addc_co_u32_e32 v93, vcc, -1, v111, vcc
	s_mov_b32 s2, 0xffffe000
	v_add_co_u32_e32 v94, vcc, s2, v110
	s_nop 1
	v_addc_co_u32_e32 v95, vcc, -1, v111, vcc
	s_mov_b32 s2, 0x2000
	v_add_co_u32_e32 v96, vcc, s2, v110
	s_nop 1
	v_addc_co_u32_e32 v97, vcc, 0, v111, vcc
	s_mov_b32 s2, 0x4000
	v_add_co_u32_e32 v98, vcc, s2, v110
	s_nop 1
	v_addc_co_u32_e32 v99, vcc, 0, v111, vcc
	s_mov_b32 s2, 0x6000
	v_add_co_u32_e32 v100, vcc, s2, v110
	s_nop 1
	v_addc_co_u32_e32 v101, vcc, 0, v111, vcc
	s_mov_b32 s2, 0x8000
	v_add_co_u32_e32 v102, vcc, s2, v110
	s_nop 1
	v_addc_co_u32_e32 v103, vcc, 0, v111, vcc
	s_mov_b32 s2, 0xa000
	v_add_co_u32_e32 v104, vcc, s2, v110
	s_nop 1
	v_addc_co_u32_e32 v105, vcc, 0, v111, vcc
	s_mov_b32 s2, 0xc000
	v_add_co_u32_e32 v106, vcc, s2, v110
	s_nop 1
	v_addc_co_u32_e32 v107, vcc, 0, v111, vcc
	s_mov_b32 s2, 0xe000
	v_add_co_u32_e32 v108, vcc, s2, v110
	s_nop 1
	v_addc_co_u32_e32 v109, vcc, 0, v111, vcc
	s_mov_b32 m0, s100
	s_nop 0
	global_load_lds_dwordx4 v[62:63], off
	s_add_i32 m0, s100, 0x2000
	s_nop 0
	global_load_lds_dwordx4 v[82:83], off
	s_add_i32 m0, s100, 0x4000
	s_nop 0
	global_load_lds_dwordx4 v[84:85], off
	s_add_i32 m0, s100, 0x6000
	s_nop 0
	global_load_lds_dwordx4 v[86:87], off
	s_add_i32 m0, s100, 0x8000
	s_nop 0
	global_load_lds_dwordx4 v[88:89], off
	s_add_i32 m0, s100, 0xa000
	s_nop 0
	global_load_lds_dwordx4 v[90:91], off
	s_add_i32 m0, s100, 0xc000
	s_nop 0
	global_load_lds_dwordx4 v[92:93], off
	s_add_i32 m0, s100, 0xe000
	s_nop 0
	global_load_lds_dwordx4 v[94:95], off
	s_add_i32 m0, s100, 0x10000
	s_nop 0
	global_load_lds_dwordx4 v[110:111], off
	s_add_i32 m0, s100, 0x12000
	s_nop 0
	global_load_lds_dwordx4 v[96:97], off
	s_add_i32 m0, s100, 0x14000
	s_nop 0
	global_load_lds_dwordx4 v[98:99], off
	s_add_i32 m0, s100, 0x16000
	s_nop 0
	global_load_lds_dwordx4 v[100:101], off
	s_add_i32 m0, s100, 0x18000
	s_nop 0
	global_load_lds_dwordx4 v[102:103], off
	s_add_i32 m0, s100, 0x1a000
	s_nop 0
	global_load_lds_dwordx4 v[104:105], off
	s_add_i32 m0, s100, 0x1c000
	s_nop 0
	global_load_lds_dwordx4 v[106:107], off
	s_add_i32 m0, s100, 0x1e000
	s_nop 0
	global_load_lds_dwordx4 v[108:109], off
	s_waitcnt vmcnt(0)

; __global__ void __launch_bounds__(512, 2) mk_fwd(Args args) {
	.amdhsa_kernel _Z6mk_fwd4Args
		.amdhsa_group_segment_fixed_size 0
		.amdhsa_private_segment_fixed_size 0
		.amdhsa_kernarg_size 504
		.amdhsa_user_sgpr_count 2
		.amdhsa_user_sgpr_dispatch_ptr 0
		.amdhsa_user_sgpr_queue_ptr 0
		.amdhsa_user_sgpr_kernarg_segment_ptr 1
		.amdhsa_user_sgpr_dispatch_id 0
		.amdhsa_user_sgpr_kernarg_preload_length 0
		.amdhsa_user_sgpr_kernarg_preload_offset 0
		.amdhsa_user_sgpr_private_segment_size 0
		.amdhsa_uses_dynamic_stack 0
		.amdhsa_enable_private_segment 0
		.amdhsa_system_sgpr_workgroup_id_x 1
		.amdhsa_system_sgpr_workgroup_id_y 0
		.amdhsa_system_sgpr_workgroup_id_z 0
		.amdhsa_system_sgpr_workgroup_info 0
		.amdhsa_system_vgpr_workitem_id 2
		.amdhsa_next_free_vgpr 256
		.amdhsa_next_free_sgpr 102
		.amdhsa_accum_offset 256
		.amdhsa_reserve_vcc 1
		.amdhsa_float_round_mode_32 0
		.amdhsa_float_round_mode_16_64 0
		.amdhsa_float_denorm_mode_32 3
		.amdhsa_float_denorm_mode_16_64 3
		.amdhsa_dx10_clamp 1
		.amdhsa_ieee_mode 1
		.amdhsa_fp16_overflow 0
		.amdhsa_tg_split 0
		.amdhsa_exception_fp_ieee_invalid_op 0
		.amdhsa_exception_fp_denorm_src 0
		.amdhsa_exception_fp_ieee_div_zero 0
		.amdhsa_exception_fp_ieee_overflow 0
		.amdhsa_exception_fp_ieee_underflow 0
		.amdhsa_exception_fp_ieee_inexact 0
		.amdhsa_exception_int_div_zero 0
	.end_amdhsa_kernel

; __global__ void __launch_bounds__(512, 2) mk_fwd(Args args) {
amdhsa.kernels:
  - .agpr_count:     0
    .args:
      - .offset:         0
        .size:           248
        .value_kind:     by_value
      - .offset:         248
        .size:           4
        .value_kind:     hidden_block_count_x
      - .offset:         252
        .size:           4
        .value_kind:     hidden_block_count_y
      - .offset:         256
        .size:           4
        .value_kind:     hidden_block_count_z
      - .offset:         260
        .size:           2
        .value_kind:     hidden_group_size_x
      - .offset:         262
        .size:           2
        .value_kind:     hidden_group_size_y
      - .offset:         264
        .size:           2
        .value_kind:     hidden_group_size_z
      - .offset:         266
        .size:           2
        .value_kind:     hidden_remainder_x
      - .offset:         268
        .size:           2
        .value_kind:     hidden_remainder_y
      - .offset:         270
        .size:           2
        .value_kind:     hidden_remainder_z
      - .offset:         288
        .size:           8
        .value_kind:     hidden_global_offset_x
      - .offset:         296
        .size:           8
        .value_kind:     hidden_global_offset_y
      - .offset:         304
        .size:           8
        .value_kind:     hidden_global_offset_z
      - .offset:         312
        .size:           2
        .value_kind:     hidden_grid_dims
      - .offset:         336
        .size:           8
        .value_kind:     hidden_multigrid_sync_arg
      - .offset:         368
        .size:           4
        .value_kind:     hidden_dynamic_lds_size
    .group_segment_fixed_size: 0
    .kernarg_segment_align: 8
    .kernarg_segment_size: 504
    .language:       OpenCL C
    .language_version:
      - 2
      - 0
    .max_flat_workgroup_size: 512
    .name:           _Z6mk_fwd4Args
    .private_segment_fixed_size: 0
    .sgpr_count:     108
    .sgpr_spill_count: 204
    .symbol:         _Z6mk_fwd4Args.kd
    .uniform_work_group_size: 1
    .uses_dynamic_stack: false
    .vgpr_count:     256
    .vgpr_spill_count: 0
    .wavefront_size: 64
